# conv phase: straight-line 31-tap path for rows away from the sequence ends (no per-tap boundary logic, all row loads issued up front); on top of v15
# speedup vs baseline: 1.0109x; 1.0067x over previous
; #define LAS __attribute__((address_space(3)))
; #define GAS __attribute__((address_space(1)))
; DI float bflo(unsigned w) { return __uint_as_float(w << 16); }
; DI float bfhi(unsigned w) { return __uint_as_float(w & 0xffff0000u); }
; DI void phase_conv(const Ctx& C) {
;     ...
;     for (int row = row0 + C.wave; row < row1; row += 8) {
;         int sb, l, L;
;         if (row < MX) { sb = row & ~8191; l = row & 8191; L = SEQ; } else { sb = MX + ((row - MX) & ~255); l = (row - MX) & 255; L = CTX; }
;         f32x4 a0 = bias0, a1 = bias1;
; #pragma unroll 8
;         for (int tap = 0; tap < 31; ++tap) {
;             const int lp = l + tap - 15; const bool ok = lp >= 0 && lp < L; const int lc = ok ? lp : l;
;             const u32x4 u = *(const GAS u32x4*)(UG + (size_t)(sb + lc) * 512 + c0);
;             const float z = ok ? 1.0f : 0.0f;
;             const f32x4 w0 = *(const LAS f32x4*)(cw + tap * 512 + c0) * z, w1 = *(const LAS f32x4*)(cw + tap * 512 + c0 + 4) * z;
;             a0 += w0 * (f32x4){bflo(u.x), bfhi(u.x), bflo(u.y), bfhi(u.y)};
;             a1 += w1 * (f32x4){bflo(u.z), bfhi(u.z), bflo(u.w), bfhi(u.w)};
;         }
.LBB0_616:
	s_cmp_lt_i32 s2, 0x8000
	s_cselect_b32 s0, s6, 0xff
	s_cselect_b32 s1, s7, 0x7fffff00
	s_waitcnt vmcnt(5)
	v_mov_b64_e32 v[28:29], v[4:5]
	s_waitcnt vmcnt(1)
	v_mov_b64_e32 v[32:33], v[20:21]
	s_cselect_b32 s3, s5, 0x100
	s_and_b32 s9, s0, s2
	s_and_b32 s10, s1, s2
	v_mov_b32_e32 v54, v52
	v_mov_b64_e32 v[26:27], v[2:3]
	v_mov_b64_e32 v[30:31], v[18:19]
	s_cmp_lt_u32 s9, 15
	s_cbranch_scc1 .Lconv_slow
	s_add_i32 s11, s9, 15
	s_cmp_ge_i32 s11, s3
	s_cbranch_scc1 .Lconv_slow
	s_add_i32 s12, s9, s10
	s_add_i32 s12, s12, -15
	s_ashr_i32 s13, s12, 31
	s_lshl_b64 s[12:13], s[12:13], 10
	v_mov_b32_e32 v40, v2
	v_mov_b32_e32 v41, v3
	v_mov_b32_e32 v38, v4
	v_mov_b32_e32 v39, v5
	v_mov_b32_e32 v44, v18
	v_mov_b32_e32 v45, v19
	v_mov_b32_e32 v42, v20
	v_mov_b32_e32 v43, v21
	v_lshl_add_u64 v[96:97], v[34:35], 0, s[12:13]
	global_load_dwordx4 v[100:103], v[96:97], off
	global_load_dwordx4 v[104:107], v[96:97], off offset:1024
	global_load_dwordx4 v[108:111], v[96:97], off offset:2048
	global_load_dwordx4 v[112:115], v[96:97], off offset:3072
	s_add_u32 s12, s12, 0x1000
	s_addc_u32 s13, s13, 0
	v_lshl_add_u64 v[96:97], v[34:35], 0, s[12:13]
	global_load_dwordx4 v[116:119], v[96:97], off
	global_load_dwordx4 v[120:123], v[96:97], off offset:1024
	global_load_dwordx4 v[124:127], v[96:97], off offset:2048
	global_load_dwordx4 v[128:131], v[96:97], off offset:3072
	s_add_u32 s12, s12, 0x1000
	s_addc_u32 s13, s13, 0
	v_lshl_add_u64 v[96:97], v[34:35], 0, s[12:13]
	global_load_dwordx4 v[132:135], v[96:97], off
	global_load_dwordx4 v[136:139], v[96:97], off offset:1024
	global_load_dwordx4 v[140:143], v[96:97], off offset:2048
	global_load_dwordx4 v[144:147], v[96:97], off offset:3072
	s_add_u32 s12, s12, 0x1000
	s_addc_u32 s13, s13, 0
	v_lshl_add_u64 v[96:97], v[34:35], 0, s[12:13]
	global_load_dwordx4 v[148:151], v[96:97], off
	global_load_dwordx4 v[152:155], v[96:97], off offset:1024
	global_load_dwordx4 v[156:159], v[96:97], off offset:2048
	global_load_dwordx4 v[160:163], v[96:97], off offset:3072
	s_add_u32 s12, s12, 0x1000
	s_addc_u32 s13, s13, 0
	v_lshl_add_u64 v[96:97], v[34:35], 0, s[12:13]
	global_load_dwordx4 v[164:167], v[96:97], off
	global_load_dwordx4 v[168:171], v[96:97], off offset:1024
	global_load_dwordx4 v[172:175], v[96:97], off offset:2048
	global_load_dwordx4 v[176:179], v[96:97], off offset:3072
	s_add_u32 s12, s12, 0x1000
	s_addc_u32 s13, s13, 0
	v_lshl_add_u64 v[96:97], v[34:35], 0, s[12:13]
	global_load_dwordx4 v[180:183], v[96:97], off
	global_load_dwordx4 v[184:187], v[96:97], off offset:1024
	global_load_dwordx4 v[188:191], v[96:97], off offset:2048
	global_load_dwordx4 v[192:195], v[96:97], off offset:3072
	s_add_u32 s12, s12, 0x1000
	s_addc_u32 s13, s13, 0
	v_lshl_add_u64 v[96:97], v[34:35], 0, s[12:13]
	global_load_dwordx4 v[196:199], v[96:97], off
	global_load_dwordx4 v[200:203], v[96:97], off offset:1024
	global_load_dwordx4 v[204:207], v[96:97], off offset:2048
	global_load_dwordx4 v[208:211], v[96:97], off offset:3072
	s_add_u32 s12, s12, 0x1000
	s_addc_u32 s13, s13, 0
	v_lshl_add_u64 v[96:97], v[34:35], 0, s[12:13]
	global_load_dwordx4 v[212:215], v[96:97], off
	global_load_dwordx4 v[216:219], v[96:97], off offset:1024
	global_load_dwordx4 v[220:223], v[96:97], off offset:2048
	ds_read_b128 v[224:227], v52
	ds_read_b128 v[228:231], v52 offset:16
	ds_read_b128 v[238:241], v52 offset:2048
	ds_read_b128 v[242:245], v52 offset:2064
	ds_read_b128 v[246:249], v52 offset:4096
	ds_read_b128 v[250:253], v52 offset:4112
	s_waitcnt vmcnt(30) lgkmcnt(4)
	v_lshlrev_b32_e32 v94, 16, v100
	v_and_b32_e32 v95, 0xffff0000, v100
	v_lshlrev_b32_e32 v96, 16, v101
	v_and_b32_e32 v97, 0xffff0000, v101
	v_lshlrev_b32_e32 v98, 16, v102
	v_and_b32_e32 v99, 0xffff0000, v102
	v_lshlrev_b32_e32 v254, 16, v103
	v_and_b32_e32 v255, 0xffff0000, v103
	v_pk_fma_f32 v[40:41], v[224:225], v[94:95], v[40:41]
	v_pk_fma_f32 v[38:39], v[226:227], v[96:97], v[38:39]
	v_pk_fma_f32 v[44:45], v[228:229], v[98:99], v[44:45]
	v_pk_fma_f32 v[42:43], v[230:231], v[254:255], v[42:43]
	ds_read_b128 v[224:227], v52 offset:6144
	ds_read_b128 v[228:231], v52 offset:6160
	s_waitcnt vmcnt(29) lgkmcnt(4)
	v_lshlrev_b32_e32 v94, 16, v104
	v_and_b32_e32 v95, 0xffff0000, v104
	v_lshlrev_b32_e32 v96, 16, v105
	v_and_b32_e32 v97, 0xffff0000, v105
	v_lshlrev_b32_e32 v98, 16, v106
	v_and_b32_e32 v99, 0xffff0000, v106
	v_lshlrev_b32_e32 v254, 16, v107
	v_and_b32_e32 v255, 0xffff0000, v107
	v_pk_fma_f32 v[40:41], v[238:239], v[94:95], v[40:41]
	v_pk_fma_f32 v[38:39], v[240:241], v[96:97], v[38:39]
	v_pk_fma_f32 v[44:45], v[242:243], v[98:99], v[44:45]
	v_pk_fma_f32 v[42:43], v[244:245], v[254:255], v[42:43]
	ds_read_b128 v[238:241], v52 offset:8192
	ds_read_b128 v[242:245], v52 offset:8208
	s_waitcnt vmcnt(28) lgkmcnt(4)
	v_lshlrev_b32_e32 v94, 16, v108
	v_and_b32_e32 v95, 0xffff0000, v108
	v_lshlrev_b32_e32 v96, 16, v109
	v_and_b32_e32 v97, 0xffff0000, v109
	v_lshlrev_b32_e32 v98, 16, v110
	v_and_b32_e32 v99, 0xffff0000, v110
	v_lshlrev_b32_e32 v254, 16, v111
	v_and_b32_e32 v255, 0xffff0000, v111
	v_pk_fma_f32 v[40:41], v[246:247], v[94:95], v[40:41]
	v_pk_fma_f32 v[38:39], v[248:249], v[96:97], v[38:39]
	v_pk_fma_f32 v[44:45], v[250:251], v[98:99], v[44:45]
	v_pk_fma_f32 v[42:43], v[252:253], v[254:255], v[42:43]
	ds_read_b128 v[246:249], v52 offset:10240
	ds_read_b128 v[250:253], v52 offset:10256
	s_waitcnt vmcnt(27) lgkmcnt(4)
; #define LAS __attribute__((address_space(3)))
; #define GAS __attribute__((address_space(1)))
; DI float bflo(unsigned w) { return __uint_as_float(w << 16); }
; DI float bfhi(unsigned w) { return __uint_as_float(w & 0xffff0000u); }
; DI void phase_conv(const Ctx& C) {
;     ...
;         for (int tap = 0; tap < 31; ++tap) {
;             const int lp = l + tap - 15; const bool ok = lp >= 0 && lp < L; const int lc = ok ? lp : l;
;             const u32x4 u = *(const GAS u32x4*)(UG + (size_t)(sb + lc) * 512 + c0);
;             const float z = ok ? 1.0f : 0.0f;
;             const f32x4 w0 = *(const LAS f32x4*)(cw + tap * 512 + c0) * z, w1 = *(const LAS f32x4*)(cw + tap * 512 + c0 + 4) * z;
;             a0 += w0 * (f32x4){bflo(u.x), bfhi(u.x), bflo(u.y), bfhi(u.y)};
;             a1 += w1 * (f32x4){bflo(u.z), bfhi(u.z), bflo(u.w), bfhi(u.w)};
;         }
	v_lshlrev_b32_e32 v94, 16, v112
	v_and_b32_e32 v95, 0xffff0000, v112
	v_lshlrev_b32_e32 v96, 16, v113
	v_and_b32_e32 v97, 0xffff0000, v113
	v_lshlrev_b32_e32 v98, 16, v114
	v_and_b32_e32 v99, 0xffff0000, v114
	v_lshlrev_b32_e32 v254, 16, v115
	v_and_b32_e32 v255, 0xffff0000, v115
	v_pk_fma_f32 v[40:41], v[224:225], v[94:95], v[40:41]
	v_pk_fma_f32 v[38:39], v[226:227], v[96:97], v[38:39]
	v_pk_fma_f32 v[44:45], v[228:229], v[98:99], v[44:45]
	v_pk_fma_f32 v[42:43], v[230:231], v[254:255], v[42:43]
	ds_read_b128 v[224:227], v52 offset:12288
	ds_read_b128 v[228:231], v52 offset:12304
	s_waitcnt vmcnt(26) lgkmcnt(4)
	v_lshlrev_b32_e32 v94, 16, v116
	v_and_b32_e32 v95, 0xffff0000, v116
	v_lshlrev_b32_e32 v96, 16, v117
	v_and_b32_e32 v97, 0xffff0000, v117
	v_lshlrev_b32_e32 v98, 16, v118
	v_and_b32_e32 v99, 0xffff0000, v118
	v_lshlrev_b32_e32 v254, 16, v119
	v_and_b32_e32 v255, 0xffff0000, v119
	v_pk_fma_f32 v[40:41], v[238:239], v[94:95], v[40:41]
	v_pk_fma_f32 v[38:39], v[240:241], v[96:97], v[38:39]
	v_pk_fma_f32 v[44:45], v[242:243], v[98:99], v[44:45]
	v_pk_fma_f32 v[42:43], v[244:245], v[254:255], v[42:43]
	ds_read_b128 v[238:241], v52 offset:14336
	ds_read_b128 v[242:245], v52 offset:14352
	s_waitcnt vmcnt(25) lgkmcnt(4)
	v_lshlrev_b32_e32 v94, 16, v120
	v_and_b32_e32 v95, 0xffff0000, v120
	v_lshlrev_b32_e32 v96, 16, v121
	v_and_b32_e32 v97, 0xffff0000, v121
	v_lshlrev_b32_e32 v98, 16, v122
	v_and_b32_e32 v99, 0xffff0000, v122
	v_lshlrev_b32_e32 v254, 16, v123
	v_and_b32_e32 v255, 0xffff0000, v123
	v_pk_fma_f32 v[40:41], v[246:247], v[94:95], v[40:41]
	v_pk_fma_f32 v[38:39], v[248:249], v[96:97], v[38:39]
	v_pk_fma_f32 v[44:45], v[250:251], v[98:99], v[44:45]
	v_pk_fma_f32 v[42:43], v[252:253], v[254:255], v[42:43]
	ds_read_b128 v[246:249], v52 offset:16384
	ds_read_b128 v[250:253], v52 offset:16400
	s_waitcnt vmcnt(24) lgkmcnt(4)
	v_lshlrev_b32_e32 v94, 16, v124
	v_and_b32_e32 v95, 0xffff0000, v124
	v_lshlrev_b32_e32 v96, 16, v125
	v_and_b32_e32 v97, 0xffff0000, v125
	v_lshlrev_b32_e32 v98, 16, v126
	v_and_b32_e32 v99, 0xffff0000, v126
	v_lshlrev_b32_e32 v254, 16, v127
	v_and_b32_e32 v255, 0xffff0000, v127
	v_pk_fma_f32 v[40:41], v[224:225], v[94:95], v[40:41]
	v_pk_fma_f32 v[38:39], v[226:227], v[96:97], v[38:39]
	v_pk_fma_f32 v[44:45], v[228:229], v[98:99], v[44:45]
	v_pk_fma_f32 v[42:43], v[230:231], v[254:255], v[42:43]
	ds_read_b128 v[224:227], v52 offset:18432
	ds_read_b128 v[228:231], v52 offset:18448
	s_waitcnt vmcnt(23) lgkmcnt(4)
	v_lshlrev_b32_e32 v94, 16, v128
	v_and_b32_e32 v95, 0xffff0000, v128
	v_lshlrev_b32_e32 v96, 16, v129
	v_and_b32_e32 v97, 0xffff0000, v129
	v_lshlrev_b32_e32 v98, 16, v130
	v_and_b32_e32 v99, 0xffff0000, v130
	v_lshlrev_b32_e32 v254, 16, v131
	v_and_b32_e32 v255, 0xffff0000, v131
	v_pk_fma_f32 v[40:41], v[238:239], v[94:95], v[40:41]
	v_pk_fma_f32 v[38:39], v[240:241], v[96:97], v[38:39]
	v_pk_fma_f32 v[44:45], v[242:243], v[98:99], v[44:45]
	v_pk_fma_f32 v[42:43], v[244:245], v[254:255], v[42:43]
	ds_read_b128 v[238:241], v52 offset:20480
	ds_read_b128 v[242:245], v52 offset:20496
	s_waitcnt vmcnt(22) lgkmcnt(4)
	v_lshlrev_b32_e32 v94, 16, v132
	v_and_b32_e32 v95, 0xffff0000, v132
	v_lshlrev_b32_e32 v96, 16, v133
	v_and_b32_e32 v97, 0xffff0000, v133
	v_lshlrev_b32_e32 v98, 16, v134
	v_and_b32_e32 v99, 0xffff0000, v134
	v_lshlrev_b32_e32 v254, 16, v135
	v_and_b32_e32 v255, 0xffff0000, v135
	v_pk_fma_f32 v[40:41], v[246:247], v[94:95], v[40:41]
	v_pk_fma_f32 v[38:39], v[248:249], v[96:97], v[38:39]
	v_pk_fma_f32 v[44:45], v[250:251], v[98:99], v[44:45]
	v_pk_fma_f32 v[42:43], v[252:253], v[254:255], v[42:43]
	ds_read_b128 v[246:249], v52 offset:22528
	ds_read_b128 v[250:253], v52 offset:22544
	s_waitcnt vmcnt(21) lgkmcnt(4)
	v_lshlrev_b32_e32 v94, 16, v136
	v_and_b32_e32 v95, 0xffff0000, v136
	v_lshlrev_b32_e32 v96, 16, v137
	v_and_b32_e32 v97, 0xffff0000, v137
	v_lshlrev_b32_e32 v98, 16, v138
	v_and_b32_e32 v99, 0xffff0000, v138
	v_lshlrev_b32_e32 v254, 16, v139
	v_and_b32_e32 v255, 0xffff0000, v139
	v_pk_fma_f32 v[40:41], v[224:225], v[94:95], v[40:41]
	v_pk_fma_f32 v[38:39], v[226:227], v[96:97], v[38:39]
	v_pk_fma_f32 v[44:45], v[228:229], v[98:99], v[44:45]
	v_pk_fma_f32 v[42:43], v[230:231], v[254:255], v[42:43]
	ds_read_b128 v[224:227], v52 offset:24576
	ds_read_b128 v[228:231], v52 offset:24592
	s_waitcnt vmcnt(20) lgkmcnt(4)
	v_lshlrev_b32_e32 v94, 16, v140
	v_and_b32_e32 v95, 0xffff0000, v140
	v_lshlrev_b32_e32 v96, 16, v141
	v_and_b32_e32 v97, 0xffff0000, v141
	v_lshlrev_b32_e32 v98, 16, v142
	v_and_b32_e32 v99, 0xffff0000, v142
	v_lshlrev_b32_e32 v254, 16, v143
	v_and_b32_e32 v255, 0xffff0000, v143
	v_pk_fma_f32 v[40:41], v[238:239], v[94:95], v[40:41]
	v_pk_fma_f32 v[38:39], v[240:241], v[96:97], v[38:39]
	v_pk_fma_f32 v[44:45], v[242:243], v[98:99], v[44:45]
	v_pk_fma_f32 v[42:43], v[244:245], v[254:255], v[42:43]
	ds_read_b128 v[238:241], v52 offset:26624
	ds_read_b128 v[242:245], v52 offset:26640
	s_waitcnt vmcnt(19) lgkmcnt(4)
	v_lshlrev_b32_e32 v94, 16, v144
	v_and_b32_e32 v95, 0xffff0000, v144
	v_lshlrev_b32_e32 v96, 16, v145
	v_and_b32_e32 v97, 0xffff0000, v145
	v_lshlrev_b32_e32 v98, 16, v146
	v_and_b32_e32 v99, 0xffff0000, v146
	v_lshlrev_b32_e32 v254, 16, v147
	v_and_b32_e32 v255, 0xffff0000, v147
	v_pk_fma_f32 v[40:41], v[246:247], v[94:95], v[40:41]
	v_pk_fma_f32 v[38:39], v[248:249], v[96:97], v[38:39]
	v_pk_fma_f32 v[44:45], v[250:251], v[98:99], v[44:45]
	v_pk_fma_f32 v[42:43], v[252:253], v[254:255], v[42:43]
	ds_read_b128 v[246:249], v52 offset:28672
	ds_read_b128 v[250:253], v52 offset:28688
	s_waitcnt vmcnt(18) lgkmcnt(4)
; #define LAS __attribute__((address_space(3)))
; #define GAS __attribute__((address_space(1)))
; DI float bflo(unsigned w) { return __uint_as_float(w << 16); }
; DI float bfhi(unsigned w) { return __uint_as_float(w & 0xffff0000u); }
; DI void phase_conv(const Ctx& C) {
;     ...
;         for (int tap = 0; tap < 31; ++tap) {
;             const int lp = l + tap - 15; const bool ok = lp >= 0 && lp < L; const int lc = ok ? lp : l;
;             const u32x4 u = *(const GAS u32x4*)(UG + (size_t)(sb + lc) * 512 + c0);
;             const float z = ok ? 1.0f : 0.0f;
;             const f32x4 w0 = *(const LAS f32x4*)(cw + tap * 512 + c0) * z, w1 = *(const LAS f32x4*)(cw + tap * 512 + c0 + 4) * z;
;             a0 += w0 * (f32x4){bflo(u.x), bfhi(u.x), bflo(u.y), bfhi(u.y)};
;             a1 += w1 * (f32x4){bflo(u.z), bfhi(u.z), bflo(u.w), bfhi(u.w)};
;         }
	v_lshlrev_b32_e32 v94, 16, v148
	v_and_b32_e32 v95, 0xffff0000, v148
	v_lshlrev_b32_e32 v96, 16, v149
	v_and_b32_e32 v97, 0xffff0000, v149
	v_lshlrev_b32_e32 v98, 16, v150
	v_and_b32_e32 v99, 0xffff0000, v150
	v_lshlrev_b32_e32 v254, 16, v151
	v_and_b32_e32 v255, 0xffff0000, v151
	v_pk_fma_f32 v[40:41], v[224:225], v[94:95], v[40:41]
	v_pk_fma_f32 v[38:39], v[226:227], v[96:97], v[38:39]
	v_pk_fma_f32 v[44:45], v[228:229], v[98:99], v[44:45]
	v_pk_fma_f32 v[42:43], v[230:231], v[254:255], v[42:43]
	ds_read_b128 v[224:227], v52 offset:30720
	ds_read_b128 v[228:231], v52 offset:30736
	s_waitcnt vmcnt(17) lgkmcnt(4)
	v_lshlrev_b32_e32 v94, 16, v152
	v_and_b32_e32 v95, 0xffff0000, v152
	v_lshlrev_b32_e32 v96, 16, v153
	v_and_b32_e32 v97, 0xffff0000, v153
	v_lshlrev_b32_e32 v98, 16, v154
	v_and_b32_e32 v99, 0xffff0000, v154
	v_lshlrev_b32_e32 v254, 16, v155
	v_and_b32_e32 v255, 0xffff0000, v155
	v_pk_fma_f32 v[40:41], v[238:239], v[94:95], v[40:41]
	v_pk_fma_f32 v[38:39], v[240:241], v[96:97], v[38:39]
	v_pk_fma_f32 v[44:45], v[242:243], v[98:99], v[44:45]
	v_pk_fma_f32 v[42:43], v[244:245], v[254:255], v[42:43]
	ds_read_b128 v[238:241], v52 offset:32768
	ds_read_b128 v[242:245], v52 offset:32784
	s_waitcnt vmcnt(16) lgkmcnt(4)
	v_lshlrev_b32_e32 v94, 16, v156
	v_and_b32_e32 v95, 0xffff0000, v156
	v_lshlrev_b32_e32 v96, 16, v157
	v_and_b32_e32 v97, 0xffff0000, v157
	v_lshlrev_b32_e32 v98, 16, v158
	v_and_b32_e32 v99, 0xffff0000, v158
	v_lshlrev_b32_e32 v254, 16, v159
	v_and_b32_e32 v255, 0xffff0000, v159
	v_pk_fma_f32 v[40:41], v[246:247], v[94:95], v[40:41]
	v_pk_fma_f32 v[38:39], v[248:249], v[96:97], v[38:39]
	v_pk_fma_f32 v[44:45], v[250:251], v[98:99], v[44:45]
	v_pk_fma_f32 v[42:43], v[252:253], v[254:255], v[42:43]
	ds_read_b128 v[246:249], v52 offset:34816
	ds_read_b128 v[250:253], v52 offset:34832
	s_waitcnt vmcnt(15) lgkmcnt(4)
	v_lshlrev_b32_e32 v94, 16, v160
	v_and_b32_e32 v95, 0xffff0000, v160
	v_lshlrev_b32_e32 v96, 16, v161
	v_and_b32_e32 v97, 0xffff0000, v161
	v_lshlrev_b32_e32 v98, 16, v162
	v_and_b32_e32 v99, 0xffff0000, v162
	v_lshlrev_b32_e32 v254, 16, v163
	v_and_b32_e32 v255, 0xffff0000, v163
	v_pk_fma_f32 v[40:41], v[224:225], v[94:95], v[40:41]
	v_pk_fma_f32 v[38:39], v[226:227], v[96:97], v[38:39]
	v_pk_fma_f32 v[44:45], v[228:229], v[98:99], v[44:45]
	v_pk_fma_f32 v[42:43], v[230:231], v[254:255], v[42:43]
	ds_read_b128 v[224:227], v52 offset:36864
	ds_read_b128 v[228:231], v52 offset:36880
	s_waitcnt vmcnt(14) lgkmcnt(4)
	v_lshlrev_b32_e32 v94, 16, v164
	v_and_b32_e32 v95, 0xffff0000, v164
	v_lshlrev_b32_e32 v96, 16, v165
	v_and_b32_e32 v97, 0xffff0000, v165
	v_lshlrev_b32_e32 v98, 16, v166
	v_and_b32_e32 v99, 0xffff0000, v166
	v_lshlrev_b32_e32 v254, 16, v167
	v_and_b32_e32 v255, 0xffff0000, v167
	v_pk_fma_f32 v[40:41], v[238:239], v[94:95], v[40:41]
	v_pk_fma_f32 v[38:39], v[240:241], v[96:97], v[38:39]
	v_pk_fma_f32 v[44:45], v[242:243], v[98:99], v[44:45]
	v_pk_fma_f32 v[42:43], v[244:245], v[254:255], v[42:43]
	ds_read_b128 v[238:241], v52 offset:38912
	ds_read_b128 v[242:245], v52 offset:38928
	s_waitcnt vmcnt(13) lgkmcnt(4)
	v_lshlrev_b32_e32 v94, 16, v168
	v_and_b32_e32 v95, 0xffff0000, v168
	v_lshlrev_b32_e32 v96, 16, v169
	v_and_b32_e32 v97, 0xffff0000, v169
	v_lshlrev_b32_e32 v98, 16, v170
	v_and_b32_e32 v99, 0xffff0000, v170
	v_lshlrev_b32_e32 v254, 16, v171
	v_and_b32_e32 v255, 0xffff0000, v171
	v_pk_fma_f32 v[40:41], v[246:247], v[94:95], v[40:41]
	v_pk_fma_f32 v[38:39], v[248:249], v[96:97], v[38:39]
	v_pk_fma_f32 v[44:45], v[250:251], v[98:99], v[44:45]
	v_pk_fma_f32 v[42:43], v[252:253], v[254:255], v[42:43]
	ds_read_b128 v[246:249], v52 offset:40960
	ds_read_b128 v[250:253], v52 offset:40976
	s_waitcnt vmcnt(12) lgkmcnt(4)
	v_lshlrev_b32_e32 v94, 16, v172
	v_and_b32_e32 v95, 0xffff0000, v172
	v_lshlrev_b32_e32 v96, 16, v173
	v_and_b32_e32 v97, 0xffff0000, v173
	v_lshlrev_b32_e32 v98, 16, v174
	v_and_b32_e32 v99, 0xffff0000, v174
	v_lshlrev_b32_e32 v254, 16, v175
	v_and_b32_e32 v255, 0xffff0000, v175
	v_pk_fma_f32 v[40:41], v[224:225], v[94:95], v[40:41]
	v_pk_fma_f32 v[38:39], v[226:227], v[96:97], v[38:39]
	v_pk_fma_f32 v[44:45], v[228:229], v[98:99], v[44:45]
	v_pk_fma_f32 v[42:43], v[230:231], v[254:255], v[42:43]
	ds_read_b128 v[224:227], v52 offset:43008
	ds_read_b128 v[228:231], v52 offset:43024
	s_waitcnt vmcnt(11) lgkmcnt(4)
	v_lshlrev_b32_e32 v94, 16, v176
	v_and_b32_e32 v95, 0xffff0000, v176
	v_lshlrev_b32_e32 v96, 16, v177
	v_and_b32_e32 v97, 0xffff0000, v177
	v_lshlrev_b32_e32 v98, 16, v178
	v_and_b32_e32 v99, 0xffff0000, v178
	v_lshlrev_b32_e32 v254, 16, v179
	v_and_b32_e32 v255, 0xffff0000, v179
	v_pk_fma_f32 v[40:41], v[238:239], v[94:95], v[40:41]
	v_pk_fma_f32 v[38:39], v[240:241], v[96:97], v[38:39]
	v_pk_fma_f32 v[44:45], v[242:243], v[98:99], v[44:45]
	v_pk_fma_f32 v[42:43], v[244:245], v[254:255], v[42:43]
	ds_read_b128 v[238:241], v52 offset:45056
	ds_read_b128 v[242:245], v52 offset:45072
	s_waitcnt vmcnt(10) lgkmcnt(4)
	v_lshlrev_b32_e32 v94, 16, v180
	v_and_b32_e32 v95, 0xffff0000, v180
	v_lshlrev_b32_e32 v96, 16, v181
	v_and_b32_e32 v97, 0xffff0000, v181
	v_lshlrev_b32_e32 v98, 16, v182
	v_and_b32_e32 v99, 0xffff0000, v182
	v_lshlrev_b32_e32 v254, 16, v183
	v_and_b32_e32 v255, 0xffff0000, v183
	v_pk_fma_f32 v[40:41], v[246:247], v[94:95], v[40:41]
	v_pk_fma_f32 v[38:39], v[248:249], v[96:97], v[38:39]
	v_pk_fma_f32 v[44:45], v[250:251], v[98:99], v[44:45]
	v_pk_fma_f32 v[42:43], v[252:253], v[254:255], v[42:43]
	ds_read_b128 v[246:249], v52 offset:47104
	ds_read_b128 v[250:253], v52 offset:47120
	s_waitcnt vmcnt(9) lgkmcnt(4)
; #define LAS __attribute__((address_space(3)))
; #define GAS __attribute__((address_space(1)))
; DI float bflo(unsigned w) { return __uint_as_float(w << 16); }
; DI float bfhi(unsigned w) { return __uint_as_float(w & 0xffff0000u); }
; DI void phase_conv(const Ctx& C) {
;     ...
;         for (int tap = 0; tap < 31; ++tap) {
;             const int lp = l + tap - 15; const bool ok = lp >= 0 && lp < L; const int lc = ok ? lp : l;
;             const u32x4 u = *(const GAS u32x4*)(UG + (size_t)(sb + lc) * 512 + c0);
;             const float z = ok ? 1.0f : 0.0f;
;             const f32x4 w0 = *(const LAS f32x4*)(cw + tap * 512 + c0) * z, w1 = *(const LAS f32x4*)(cw + tap * 512 + c0 + 4) * z;
;             a0 += w0 * (f32x4){bflo(u.x), bfhi(u.x), bflo(u.y), bfhi(u.y)};
;             a1 += w1 * (f32x4){bflo(u.z), bfhi(u.z), bflo(u.w), bfhi(u.w)};
;         }
	v_lshlrev_b32_e32 v94, 16, v184
	v_and_b32_e32 v95, 0xffff0000, v184
	v_lshlrev_b32_e32 v96, 16, v185
	v_and_b32_e32 v97, 0xffff0000, v185
	v_lshlrev_b32_e32 v98, 16, v186
	v_and_b32_e32 v99, 0xffff0000, v186
	v_lshlrev_b32_e32 v254, 16, v187
	v_and_b32_e32 v255, 0xffff0000, v187
	v_pk_fma_f32 v[40:41], v[224:225], v[94:95], v[40:41]
	v_pk_fma_f32 v[38:39], v[226:227], v[96:97], v[38:39]
	v_pk_fma_f32 v[44:45], v[228:229], v[98:99], v[44:45]
	v_pk_fma_f32 v[42:43], v[230:231], v[254:255], v[42:43]
	ds_read_b128 v[224:227], v52 offset:49152
	ds_read_b128 v[228:231], v52 offset:49168
	s_waitcnt vmcnt(8) lgkmcnt(4)
	v_lshlrev_b32_e32 v94, 16, v188
	v_and_b32_e32 v95, 0xffff0000, v188
	v_lshlrev_b32_e32 v96, 16, v189
	v_and_b32_e32 v97, 0xffff0000, v189
	v_lshlrev_b32_e32 v98, 16, v190
	v_and_b32_e32 v99, 0xffff0000, v190
	v_lshlrev_b32_e32 v254, 16, v191
	v_and_b32_e32 v255, 0xffff0000, v191
	v_pk_fma_f32 v[40:41], v[238:239], v[94:95], v[40:41]
	v_pk_fma_f32 v[38:39], v[240:241], v[96:97], v[38:39]
	v_pk_fma_f32 v[44:45], v[242:243], v[98:99], v[44:45]
	v_pk_fma_f32 v[42:43], v[244:245], v[254:255], v[42:43]
	ds_read_b128 v[238:241], v52 offset:51200
	ds_read_b128 v[242:245], v52 offset:51216
	s_waitcnt vmcnt(7) lgkmcnt(4)
	v_lshlrev_b32_e32 v94, 16, v192
	v_and_b32_e32 v95, 0xffff0000, v192
	v_lshlrev_b32_e32 v96, 16, v193
	v_and_b32_e32 v97, 0xffff0000, v193
	v_lshlrev_b32_e32 v98, 16, v194
	v_and_b32_e32 v99, 0xffff0000, v194
	v_lshlrev_b32_e32 v254, 16, v195
	v_and_b32_e32 v255, 0xffff0000, v195
	v_pk_fma_f32 v[40:41], v[246:247], v[94:95], v[40:41]
	v_pk_fma_f32 v[38:39], v[248:249], v[96:97], v[38:39]
	v_pk_fma_f32 v[44:45], v[250:251], v[98:99], v[44:45]
	v_pk_fma_f32 v[42:43], v[252:253], v[254:255], v[42:43]
	ds_read_b128 v[246:249], v52 offset:53248
	ds_read_b128 v[250:253], v52 offset:53264
	s_waitcnt vmcnt(6) lgkmcnt(4)
	v_lshlrev_b32_e32 v94, 16, v196
	v_and_b32_e32 v95, 0xffff0000, v196
	v_lshlrev_b32_e32 v96, 16, v197
	v_and_b32_e32 v97, 0xffff0000, v197
	v_lshlrev_b32_e32 v98, 16, v198
	v_and_b32_e32 v99, 0xffff0000, v198
	v_lshlrev_b32_e32 v254, 16, v199
	v_and_b32_e32 v255, 0xffff0000, v199
	v_pk_fma_f32 v[40:41], v[224:225], v[94:95], v[40:41]
	v_pk_fma_f32 v[38:39], v[226:227], v[96:97], v[38:39]
	v_pk_fma_f32 v[44:45], v[228:229], v[98:99], v[44:45]
	v_pk_fma_f32 v[42:43], v[230:231], v[254:255], v[42:43]
	ds_read_b128 v[224:227], v52 offset:55296
	ds_read_b128 v[228:231], v52 offset:55312
	s_waitcnt vmcnt(5) lgkmcnt(4)
	v_lshlrev_b32_e32 v94, 16, v200
	v_and_b32_e32 v95, 0xffff0000, v200
	v_lshlrev_b32_e32 v96, 16, v201
	v_and_b32_e32 v97, 0xffff0000, v201
	v_lshlrev_b32_e32 v98, 16, v202
	v_and_b32_e32 v99, 0xffff0000, v202
	v_lshlrev_b32_e32 v254, 16, v203
	v_and_b32_e32 v255, 0xffff0000, v203
	v_pk_fma_f32 v[40:41], v[238:239], v[94:95], v[40:41]
	v_pk_fma_f32 v[38:39], v[240:241], v[96:97], v[38:39]
	v_pk_fma_f32 v[44:45], v[242:243], v[98:99], v[44:45]
	v_pk_fma_f32 v[42:43], v[244:245], v[254:255], v[42:43]
	ds_read_b128 v[238:241], v52 offset:57344
	ds_read_b128 v[242:245], v52 offset:57360
	s_waitcnt vmcnt(4) lgkmcnt(4)
	v_lshlrev_b32_e32 v94, 16, v204
	v_and_b32_e32 v95, 0xffff0000, v204
	v_lshlrev_b32_e32 v96, 16, v205
	v_and_b32_e32 v97, 0xffff0000, v205
	v_lshlrev_b32_e32 v98, 16, v206
	v_and_b32_e32 v99, 0xffff0000, v206
	v_lshlrev_b32_e32 v254, 16, v207
	v_and_b32_e32 v255, 0xffff0000, v207
	v_pk_fma_f32 v[40:41], v[246:247], v[94:95], v[40:41]
	v_pk_fma_f32 v[38:39], v[248:249], v[96:97], v[38:39]
	v_pk_fma_f32 v[44:45], v[250:251], v[98:99], v[44:45]
	v_pk_fma_f32 v[42:43], v[252:253], v[254:255], v[42:43]
	ds_read_b128 v[246:249], v52 offset:59392
	ds_read_b128 v[250:253], v52 offset:59408
	s_waitcnt vmcnt(3) lgkmcnt(4)
	v_lshlrev_b32_e32 v94, 16, v208
	v_and_b32_e32 v95, 0xffff0000, v208
	v_lshlrev_b32_e32 v96, 16, v209
	v_and_b32_e32 v97, 0xffff0000, v209
	v_lshlrev_b32_e32 v98, 16, v210
	v_and_b32_e32 v99, 0xffff0000, v210
	v_lshlrev_b32_e32 v254, 16, v211
	v_and_b32_e32 v255, 0xffff0000, v211
	v_pk_fma_f32 v[40:41], v[224:225], v[94:95], v[40:41]
	v_pk_fma_f32 v[38:39], v[226:227], v[96:97], v[38:39]
	v_pk_fma_f32 v[44:45], v[228:229], v[98:99], v[44:45]
	v_pk_fma_f32 v[42:43], v[230:231], v[254:255], v[42:43]
	ds_read_b128 v[224:227], v52 offset:61440
	ds_read_b128 v[228:231], v52 offset:61456
	s_waitcnt vmcnt(2) lgkmcnt(4)
	v_lshlrev_b32_e32 v94, 16, v212
	v_and_b32_e32 v95, 0xffff0000, v212
	v_lshlrev_b32_e32 v96, 16, v213
	v_and_b32_e32 v97, 0xffff0000, v213
	v_lshlrev_b32_e32 v98, 16, v214
	v_and_b32_e32 v99, 0xffff0000, v214
	v_lshlrev_b32_e32 v254, 16, v215
	v_and_b32_e32 v255, 0xffff0000, v215
	v_pk_fma_f32 v[40:41], v[238:239], v[94:95], v[40:41]
	v_pk_fma_f32 v[38:39], v[240:241], v[96:97], v[38:39]
	v_pk_fma_f32 v[44:45], v[242:243], v[98:99], v[44:45]
	v_pk_fma_f32 v[42:43], v[244:245], v[254:255], v[42:43]
	s_waitcnt vmcnt(1) lgkmcnt(2)
	v_lshlrev_b32_e32 v94, 16, v216
	v_and_b32_e32 v95, 0xffff0000, v216
	v_lshlrev_b32_e32 v96, 16, v217
	v_and_b32_e32 v97, 0xffff0000, v217
	v_lshlrev_b32_e32 v98, 16, v218
	v_and_b32_e32 v99, 0xffff0000, v218
	v_lshlrev_b32_e32 v254, 16, v219
	v_and_b32_e32 v255, 0xffff0000, v219
	v_pk_fma_f32 v[40:41], v[246:247], v[94:95], v[40:41]
	v_pk_fma_f32 v[38:39], v[248:249], v[96:97], v[38:39]
	v_pk_fma_f32 v[44:45], v[250:251], v[98:99], v[44:45]
	v_pk_fma_f32 v[42:43], v[252:253], v[254:255], v[42:43]
	s_waitcnt vmcnt(0) lgkmcnt(0)
	v_lshlrev_b32_e32 v94, 16, v220
	v_and_b32_e32 v95, 0xffff0000, v220
	v_lshlrev_b32_e32 v96, 16, v221
	v_and_b32_e32 v97, 0xffff0000, v221
	v_lshlrev_b32_e32 v98, 16, v222
	v_and_b32_e32 v99, 0xffff0000, v222
	v_lshlrev_b32_e32 v254, 16, v223
	v_and_b32_e32 v255, 0xffff0000, v223
	v_pk_fma_f32 v[40:41], v[224:225], v[94:95], v[40:41]
	v_pk_fma_f32 v[38:39], v[226:227], v[96:97], v[38:39]
	v_pk_fma_f32 v[44:45], v[228:229], v[98:99], v[44:45]
	v_pk_fma_f32 v[42:43], v[230:231], v[254:255], v[42:43]
	s_branch .LBB0_615
.Lconv_slow:
	s_mov_b32 s11, 0
	s_branch .LBB0_618
